# P5 residual+norm-fold epilogue rewritten: 8 x-loads in flight, Gv precomputed once, row-sum bpermutes batched at end; stacks on P4,P8
# speedup vs baseline: 1.0235x; 1.0115x over previous
; __device__ __forceinline__ unsigned cvt_pk_bf16(float lo, float hi) { unsigned r; asm volatile("v_cvt_pk_bf16_f32 %0, %1, %2" : "=v"(r) : "v"(lo), "v"(hi)); return r; }
;     __device__ __forceinline__ void operator()(const f32x4 (&acc)[2][2][4][2], const Unit& u, int wr, int wc, int fr, int fq) const {
;         const int row0 = u.pm * BM + wr * 64 + fr, col0 = u.pn * BM + wc * 32 + 4 * fq, b = (u.pm * BM) >> 12;
;         f32x4 gv[2][2], Gv[2][2];
; #pragma unroll
;         for (int bj = 0; bj < 2; ++bj)
; #pragma unroll
;             for (int n = 0; n < 2; ++n) { const int c = col0 + bj * HALF + n * 16; gv[bj][n] = *(const f32x4*)(mod + (size_t)b * 12288 + 2 * 2048 + c);
;                 Gv[bj][n] = *(const f32x4*)(g2 + c) * (*(const f32x4*)(mod + (size_t)b * 12288 + 4 * 2048 + c) + 1.0f); }
;         float* prow = part + (size_t)(u.pn * 4 + wc) * 16384;
; #pragma unroll
;         for (int ai = 0; ai < 2; ++ai)
; #pragma unroll
;             for (int m = 0; m < 4; ++m) { const int row = row0 + ai * HALF + m * 16; const size_t off = (size_t)row * 2048 + col0; float ss = 0.f;
; #pragma unroll
;                 for (int bj = 0; bj < 2; ++bj)
; #pragma unroll
;                     for (int n = 0; n < 2; ++n) { const f32x4 bs = __builtin_nontemporal_load((const f32x4*)(base + off + bj * HALF + n * 16)); const f32x4 x1 = bs + gv[bj][n] * acc[ai][bj][m][n];
;                         *(f32x4*)(out + off + bj * HALF + n * 16) = x1; ss += (x1.x * x1.x + x1.y * x1.y) + (x1.z * x1.z + x1.w * x1.w);
;                         const f32x4 hh = x1 * Gv[bj][n]; u32x2 w; w.x = cvt_pk_bf16(hh.x, hh.y); w.y = cvt_pk_bf16(hh.z, hh.w); *(u32x2*)(A2 + off + bj * HALF + n * 16) = w; }
;                 ss += __shfl_xor(ss, 16); ss += __shfl_xor(ss, 32);
;                 if (fq == 0) prow[row] = ss; }
;     }
.LBB0_897:
	v_readlane_b32 s98, v236, 7
	v_readlane_b32 s99, v236, 8
	v_readlane_b32 s76, v236, 35
	v_readlane_b32 s77, v236, 36
	s_ashr_i32 s25, s36, 4
	s_mul_hi_i32 s27, s25, 0xc000
	s_mul_i32 s25, s25, 0xc000
	s_add_u32 s38, s68, s25
	s_addc_u32 s39, s69, s27
	s_add_u32 s40, s38, 0x8000
	s_addc_u32 s41, s39, 0
	s_add_u32 s38, s38, 0x4000
	s_addc_u32 s39, s39, 0
	v_lshl_add_u32 v164, s36, 8, v166
	v_lshl_or_b32 v165, s34, 8, v168
	v_lshlrev_b32_e32 v173, 2, v165
	v_xor_b32_e32 v216, 16, v172
	v_xor_b32_e32 v217, 32, v172
	v_lshlrev_b32_e32 v216, 2, v216
	v_lshlrev_b32_e32 v217, 2, v217
	global_load_dwordx4 v[72:75], v173, s[38:39]
	global_load_dwordx4 v[84:87], v173, s[38:39] offset:64
	global_load_dwordx4 v[92:95], v173, s[38:39] offset:512
	global_load_dwordx4 v[96:99], v173, s[38:39] offset:576
	global_load_dwordx4 v[156:159], v173, s[40:41]
	global_load_dwordx4 v[160:163], v173, s[40:41] offset:64
	global_load_dwordx4 v[174:177], v173, s[40:41] offset:512
	global_load_dwordx4 v[178:181], v173, s[40:41] offset:576
	global_load_dwordx4 v[182:185], v173, s[76:77]
	global_load_dwordx4 v[188:191], v173, s[76:77] offset:64
	global_load_dwordx4 v[192:195], v173, s[76:77] offset:512
	global_load_dwordx4 v[196:199], v173, s[76:77] offset:576
	v_lshl_add_u32 v164, v164, 13, v173
	v_mov_b32_e32 v165, v164
	v_lshrrev_b32_e32 v173, 1, v164
	global_load_dwordx4 v[200:203], v164, s[98:99] nt
	global_load_dwordx4 v[204:207], v164, s[98:99] offset:64 nt
	global_load_dwordx4 v[208:211], v164, s[98:99] offset:512 nt
	global_load_dwordx4 v[212:215], v164, s[98:99] offset:576 nt
	v_add_u32_e32 v164, 0x20000, v164
	s_waitcnt vmcnt(4)
	v_pk_add_f32 v[156:157], v[156:157], 1.0 op_sel_hi:[1,0]
	v_pk_add_f32 v[158:159], v[158:159], 1.0 op_sel_hi:[1,0]
	v_pk_mul_f32 v[182:183], v[182:183], v[156:157]
	v_pk_mul_f32 v[184:185], v[184:185], v[158:159]
	v_pk_add_f32 v[160:161], v[160:161], 1.0 op_sel_hi:[1,0]
	v_pk_add_f32 v[162:163], v[162:163], 1.0 op_sel_hi:[1,0]
	v_pk_mul_f32 v[188:189], v[188:189], v[160:161]
	v_pk_mul_f32 v[190:191], v[190:191], v[162:163]
	v_pk_add_f32 v[174:175], v[174:175], 1.0 op_sel_hi:[1,0]
	v_pk_add_f32 v[176:177], v[176:177], 1.0 op_sel_hi:[1,0]
	v_pk_mul_f32 v[192:193], v[192:193], v[174:175]
	v_pk_mul_f32 v[194:195], v[194:195], v[176:177]
	v_pk_add_f32 v[178:179], v[178:179], 1.0 op_sel_hi:[1,0]
	v_pk_add_f32 v[180:181], v[180:181], 1.0 op_sel_hi:[1,0]
	v_pk_mul_f32 v[196:197], v[196:197], v[178:179]
	v_pk_mul_f32 v[198:199], v[198:199], v[180:181]
	global_load_dwordx4 v[156:159], v164, s[98:99] nt
	global_load_dwordx4 v[160:163], v164, s[98:99] offset:64 nt
	global_load_dwordx4 v[174:177], v164, s[98:99] offset:512 nt
	global_load_dwordx4 v[178:181], v164, s[98:99] offset:576 nt
	v_add_u32_e32 v164, 0x20000, v164
	s_waitcnt vmcnt(7)
	v_pk_fma_f32 v[200:201], v[140:141], v[72:73], v[200:201]
	v_pk_fma_f32 v[202:203], v[142:143], v[74:75], v[202:203]
	global_store_dwordx4 v165, v[200:203], s[66:67]
	v_pk_mul_f32 v[140:141], v[200:201], v[182:183]
	v_pk_mul_f32 v[142:143], v[202:203], v[184:185]
	v_cvt_pk_bf16_f32 v140, v140, v141
	v_cvt_pk_bf16_f32 v141, v142, v143
	global_store_dwordx2 v173, v[140:141], s[8:9]
	v_mul_f32_e32 v142, v200, v200
	v_fmac_f32_e32 v142, v201, v201
	v_fmac_f32_e32 v142, v202, v202
	v_fmac_f32_e32 v142, v203, v203
	global_load_dwordx4 v[200:203], v164, s[98:99] nt
	s_waitcnt vmcnt(9)
	v_pk_fma_f32 v[204:205], v[136:137], v[84:85], v[204:205]
	v_pk_fma_f32 v[206:207], v[138:139], v[86:87], v[206:207]
	global_store_dwordx4 v165, v[204:207], s[66:67] offset:64
	v_pk_mul_f32 v[136:137], v[204:205], v[188:189]
	v_pk_mul_f32 v[138:139], v[206:207], v[190:191]
	v_cvt_pk_bf16_f32 v136, v136, v137
	v_cvt_pk_bf16_f32 v137, v138, v139
	global_store_dwordx2 v173, v[136:137], s[8:9] offset:32
	v_fmac_f32_e32 v142, v204, v204
	v_fmac_f32_e32 v142, v205, v205
	v_fmac_f32_e32 v142, v206, v206
	v_fmac_f32_e32 v142, v207, v207
	global_load_dwordx4 v[204:207], v164, s[98:99] offset:64 nt
	s_waitcnt vmcnt(11)
	v_pk_fma_f32 v[208:209], v[132:133], v[92:93], v[208:209]
	v_pk_fma_f32 v[210:211], v[134:135], v[94:95], v[210:211]
	global_store_dwordx4 v165, v[208:211], s[66:67] offset:512
	v_pk_mul_f32 v[132:133], v[208:209], v[192:193]
	v_pk_mul_f32 v[134:135], v[210:211], v[194:195]
	v_cvt_pk_bf16_f32 v132, v132, v133
	v_cvt_pk_bf16_f32 v133, v134, v135
	global_store_dwordx2 v173, v[132:133], s[8:9] offset:256
	v_fmac_f32_e32 v142, v208, v208
	v_fmac_f32_e32 v142, v209, v209
	v_fmac_f32_e32 v142, v210, v210
	v_fmac_f32_e32 v142, v211, v211
	global_load_dwordx4 v[208:211], v164, s[98:99] offset:512 nt
	s_waitcnt vmcnt(13)
	v_pk_fma_f32 v[212:213], v[128:129], v[96:97], v[212:213]
	v_pk_fma_f32 v[214:215], v[130:131], v[98:99], v[214:215]
	global_store_dwordx4 v165, v[212:215], s[66:67] offset:576
	v_pk_mul_f32 v[128:129], v[212:213], v[196:197]
	v_pk_mul_f32 v[130:131], v[214:215], v[198:199]
	v_cvt_pk_bf16_f32 v128, v128, v129
	v_cvt_pk_bf16_f32 v129, v130, v131
	global_store_dwordx2 v173, v[128:129], s[8:9] offset:288
	v_fmac_f32_e32 v142, v212, v212
	v_fmac_f32_e32 v142, v213, v213
	v_fmac_f32_e32 v142, v214, v214
	v_fmac_f32_e32 v142, v215, v215
	v_add_u32_e32 v165, 0x20000, v165
	v_lshrrev_b32_e32 v173, 1, v165
	global_load_dwordx4 v[212:215], v164, s[98:99] offset:576 nt
	v_add_u32_e32 v164, 0x20000, v164
	s_waitcnt vmcnt(15)
	v_pk_fma_f32 v[156:157], v[124:125], v[72:73], v[156:157]
	v_pk_fma_f32 v[158:159], v[126:127], v[74:75], v[158:159]
	global_store_dwordx4 v165, v[156:159], s[66:67]
	v_pk_mul_f32 v[124:125], v[156:157], v[182:183]
	v_pk_mul_f32 v[126:127], v[158:159], v[184:185]
	v_cvt_pk_bf16_f32 v124, v124, v125
	v_cvt_pk_bf16_f32 v125, v126, v127
	global_store_dwordx2 v173, v[124:125], s[8:9]
	v_mul_f32_e32 v126, v156, v156
	v_fmac_f32_e32 v126, v157, v157
	v_fmac_f32_e32 v126, v158, v158
	v_fmac_f32_e32 v126, v159, v159
	global_load_dwordx4 v[156:159], v164, s[98:99] nt
	s_waitcnt vmcnt(17)
; __device__ __forceinline__ unsigned cvt_pk_bf16(float lo, float hi) { unsigned r; asm volatile("v_cvt_pk_bf16_f32 %0, %1, %2" : "=v"(r) : "v"(lo), "v"(hi)); return r; }
;     __device__ __forceinline__ void operator()(const f32x4 (&acc)[2][2][4][2], const Unit& u, int wr, int wc, int fr, int fq) const {
;     ...
;             for (int m = 0; m < 4; ++m) { const int row = row0 + ai * HALF + m * 16; const size_t off = (size_t)row * 2048 + col0; float ss = 0.f;
; #pragma unroll
;                 for (int bj = 0; bj < 2; ++bj)
; #pragma unroll
;                     for (int n = 0; n < 2; ++n) { const f32x4 bs = __builtin_nontemporal_load((const f32x4*)(base + off + bj * HALF + n * 16)); const f32x4 x1 = bs + gv[bj][n] * acc[ai][bj][m][n];
;                         *(f32x4*)(out + off + bj * HALF + n * 16) = x1; ss += (x1.x * x1.x + x1.y * x1.y) + (x1.z * x1.z + x1.w * x1.w);
;                         const f32x4 hh = x1 * Gv[bj][n]; u32x2 w; w.x = cvt_pk_bf16(hh.x, hh.y); w.y = cvt_pk_bf16(hh.z, hh.w); *(u32x2*)(A2 + off + bj * HALF + n * 16) = w; }
	v_pk_fma_f32 v[160:161], v[120:121], v[84:85], v[160:161]
	v_pk_fma_f32 v[162:163], v[122:123], v[86:87], v[162:163]
	global_store_dwordx4 v165, v[160:163], s[66:67] offset:64
	v_pk_mul_f32 v[120:121], v[160:161], v[188:189]
	v_pk_mul_f32 v[122:123], v[162:163], v[190:191]
	v_cvt_pk_bf16_f32 v120, v120, v121
	v_cvt_pk_bf16_f32 v121, v122, v123
	global_store_dwordx2 v173, v[120:121], s[8:9] offset:32
	v_fmac_f32_e32 v126, v160, v160
	v_fmac_f32_e32 v126, v161, v161
	v_fmac_f32_e32 v126, v162, v162
	v_fmac_f32_e32 v126, v163, v163
	global_load_dwordx4 v[160:163], v164, s[98:99] offset:64 nt
	s_waitcnt vmcnt(19)
	v_pk_fma_f32 v[174:175], v[116:117], v[92:93], v[174:175]
	v_pk_fma_f32 v[176:177], v[118:119], v[94:95], v[176:177]
	global_store_dwordx4 v165, v[174:177], s[66:67] offset:512
	v_pk_mul_f32 v[116:117], v[174:175], v[192:193]
	v_pk_mul_f32 v[118:119], v[176:177], v[194:195]
	v_cvt_pk_bf16_f32 v116, v116, v117
	v_cvt_pk_bf16_f32 v117, v118, v119
	global_store_dwordx2 v173, v[116:117], s[8:9] offset:256
	v_fmac_f32_e32 v126, v174, v174
	v_fmac_f32_e32 v126, v175, v175
	v_fmac_f32_e32 v126, v176, v176
	v_fmac_f32_e32 v126, v177, v177
	global_load_dwordx4 v[174:177], v164, s[98:99] offset:512 nt
	s_waitcnt vmcnt(21)
	v_pk_fma_f32 v[178:179], v[112:113], v[96:97], v[178:179]
	v_pk_fma_f32 v[180:181], v[114:115], v[98:99], v[180:181]
	global_store_dwordx4 v165, v[178:181], s[66:67] offset:576
	v_pk_mul_f32 v[112:113], v[178:179], v[196:197]
	v_pk_mul_f32 v[114:115], v[180:181], v[198:199]
	v_cvt_pk_bf16_f32 v112, v112, v113
	v_cvt_pk_bf16_f32 v113, v114, v115
	global_store_dwordx2 v173, v[112:113], s[8:9] offset:288
	v_fmac_f32_e32 v126, v178, v178
	v_fmac_f32_e32 v126, v179, v179
	v_fmac_f32_e32 v126, v180, v180
	v_fmac_f32_e32 v126, v181, v181
	v_add_u32_e32 v165, 0x20000, v165
	v_lshrrev_b32_e32 v173, 1, v165
	global_load_dwordx4 v[178:181], v164, s[98:99] offset:576 nt
	v_add_u32_e32 v164, 0xa0000, v164
	s_waitcnt vmcnt(21)
	v_pk_fma_f32 v[200:201], v[108:109], v[72:73], v[200:201]
	v_pk_fma_f32 v[202:203], v[110:111], v[74:75], v[202:203]
	global_store_dwordx4 v165, v[200:203], s[66:67]
	v_pk_mul_f32 v[108:109], v[200:201], v[182:183]
	v_pk_mul_f32 v[110:111], v[202:203], v[184:185]
	v_cvt_pk_bf16_f32 v108, v108, v109
	v_cvt_pk_bf16_f32 v109, v110, v111
	global_store_dwordx2 v173, v[108:109], s[8:9]
	v_mul_f32_e32 v110, v200, v200
	v_fmac_f32_e32 v110, v201, v201
	v_fmac_f32_e32 v110, v202, v202
	v_fmac_f32_e32 v110, v203, v203
	global_load_dwordx4 v[200:203], v164, s[98:99] nt
	s_waitcnt vmcnt(21)
	v_pk_fma_f32 v[204:205], v[104:105], v[84:85], v[204:205]
	v_pk_fma_f32 v[206:207], v[106:107], v[86:87], v[206:207]
	global_store_dwordx4 v165, v[204:207], s[66:67] offset:64
	v_pk_mul_f32 v[104:105], v[204:205], v[188:189]
	v_pk_mul_f32 v[106:107], v[206:207], v[190:191]
	v_cvt_pk_bf16_f32 v104, v104, v105
	v_cvt_pk_bf16_f32 v105, v106, v107
	global_store_dwordx2 v173, v[104:105], s[8:9] offset:32
	v_fmac_f32_e32 v110, v204, v204
	v_fmac_f32_e32 v110, v205, v205
	v_fmac_f32_e32 v110, v206, v206
	v_fmac_f32_e32 v110, v207, v207
	global_load_dwordx4 v[204:207], v164, s[98:99] offset:64 nt
	s_waitcnt vmcnt(21)
	v_pk_fma_f32 v[208:209], v[100:101], v[92:93], v[208:209]
	v_pk_fma_f32 v[210:211], v[102:103], v[94:95], v[210:211]
	global_store_dwordx4 v165, v[208:211], s[66:67] offset:512
	v_pk_mul_f32 v[100:101], v[208:209], v[192:193]
	v_pk_mul_f32 v[102:103], v[210:211], v[194:195]
	v_cvt_pk_bf16_f32 v100, v100, v101
	v_cvt_pk_bf16_f32 v101, v102, v103
	global_store_dwordx2 v173, v[100:101], s[8:9] offset:256
	v_fmac_f32_e32 v110, v208, v208
	v_fmac_f32_e32 v110, v209, v209
	v_fmac_f32_e32 v110, v210, v210
	v_fmac_f32_e32 v110, v211, v211
	global_load_dwordx4 v[208:211], v164, s[98:99] offset:512 nt
	s_waitcnt vmcnt(21)
	v_pk_fma_f32 v[212:213], v[88:89], v[96:97], v[212:213]
	v_pk_fma_f32 v[214:215], v[90:91], v[98:99], v[214:215]
	global_store_dwordx4 v165, v[212:215], s[66:67] offset:576
	v_pk_mul_f32 v[88:89], v[212:213], v[196:197]
	v_pk_mul_f32 v[90:91], v[214:215], v[198:199]
	v_cvt_pk_bf16_f32 v88, v88, v89
	v_cvt_pk_bf16_f32 v89, v90, v91
	global_store_dwordx2 v173, v[88:89], s[8:9] offset:288
	v_fmac_f32_e32 v110, v212, v212
	v_fmac_f32_e32 v110, v213, v213
	v_fmac_f32_e32 v110, v214, v214
	v_fmac_f32_e32 v110, v215, v215
	v_add_u32_e32 v165, 0x20000, v165
	v_lshrrev_b32_e32 v173, 1, v165
	global_load_dwordx4 v[212:215], v164, s[98:99] offset:576 nt
	v_add_u32_e32 v164, 0x20000, v164
	s_waitcnt vmcnt(21)
	v_pk_fma_f32 v[156:157], v[80:81], v[72:73], v[156:157]
	v_pk_fma_f32 v[158:159], v[82:83], v[74:75], v[158:159]
	global_store_dwordx4 v165, v[156:159], s[66:67]
	v_pk_mul_f32 v[80:81], v[156:157], v[182:183]
	v_pk_mul_f32 v[82:83], v[158:159], v[184:185]
	v_cvt_pk_bf16_f32 v80, v80, v81
	v_cvt_pk_bf16_f32 v81, v82, v83
	global_store_dwordx2 v173, v[80:81], s[8:9]
	v_mul_f32_e32 v82, v156, v156
	v_fmac_f32_e32 v82, v157, v157
	v_fmac_f32_e32 v82, v158, v158
	v_fmac_f32_e32 v82, v159, v159
	global_load_dwordx4 v[156:159], v164, s[98:99] nt
	s_waitcnt vmcnt(21)
	v_pk_fma_f32 v[160:161], v[76:77], v[84:85], v[160:161]
	v_pk_fma_f32 v[162:163], v[78:79], v[86:87], v[162:163]
	global_store_dwordx4 v165, v[160:163], s[66:67] offset:64
	v_pk_mul_f32 v[76:77], v[160:161], v[188:189]
	v_pk_mul_f32 v[78:79], v[162:163], v[190:191]
	v_cvt_pk_bf16_f32 v76, v76, v77
	v_cvt_pk_bf16_f32 v77, v78, v79
	global_store_dwordx2 v173, v[76:77], s[8:9] offset:32
	v_fmac_f32_e32 v82, v160, v160
	v_fmac_f32_e32 v82, v161, v161
	v_fmac_f32_e32 v82, v162, v162
	v_fmac_f32_e32 v82, v163, v163
	global_load_dwordx4 v[160:163], v164, s[98:99] offset:64 nt
	s_waitcnt vmcnt(21)
; __device__ __forceinline__ unsigned cvt_pk_bf16(float lo, float hi) { unsigned r; asm volatile("v_cvt_pk_bf16_f32 %0, %1, %2" : "=v"(r) : "v"(lo), "v"(hi)); return r; }
;     __device__ __forceinline__ void operator()(const f32x4 (&acc)[2][2][4][2], const Unit& u, int wr, int wc, int fr, int fq) const {
;     ...
;             for (int m = 0; m < 4; ++m) { const int row = row0 + ai * HALF + m * 16; const size_t off = (size_t)row * 2048 + col0; float ss = 0.f;
; #pragma unroll
;                 for (int bj = 0; bj < 2; ++bj)
; #pragma unroll
;                     for (int n = 0; n < 2; ++n) { const f32x4 bs = __builtin_nontemporal_load((const f32x4*)(base + off + bj * HALF + n * 16)); const f32x4 x1 = bs + gv[bj][n] * acc[ai][bj][m][n];
;                         *(f32x4*)(out + off + bj * HALF + n * 16) = x1; ss += (x1.x * x1.x + x1.y * x1.y) + (x1.z * x1.z + x1.w * x1.w);
;                         const f32x4 hh = x1 * Gv[bj][n]; u32x2 w; w.x = cvt_pk_bf16(hh.x, hh.y); w.y = cvt_pk_bf16(hh.z, hh.w); *(u32x2*)(A2 + off + bj * HALF + n * 16) = w; }
	v_pk_fma_f32 v[174:175], v[68:69], v[92:93], v[174:175]
	v_pk_fma_f32 v[176:177], v[70:71], v[94:95], v[176:177]
	global_store_dwordx4 v165, v[174:177], s[66:67] offset:512
	v_pk_mul_f32 v[68:69], v[174:175], v[192:193]
	v_pk_mul_f32 v[70:71], v[176:177], v[194:195]
	v_cvt_pk_bf16_f32 v68, v68, v69
	v_cvt_pk_bf16_f32 v69, v70, v71
	global_store_dwordx2 v173, v[68:69], s[8:9] offset:256
	v_fmac_f32_e32 v82, v174, v174
	v_fmac_f32_e32 v82, v175, v175
	v_fmac_f32_e32 v82, v176, v176
	v_fmac_f32_e32 v82, v177, v177
	global_load_dwordx4 v[174:177], v164, s[98:99] offset:512 nt
	s_waitcnt vmcnt(21)
	v_pk_fma_f32 v[178:179], v[64:65], v[96:97], v[178:179]
	v_pk_fma_f32 v[180:181], v[66:67], v[98:99], v[180:181]
	global_store_dwordx4 v165, v[178:181], s[66:67] offset:576
	v_pk_mul_f32 v[64:65], v[178:179], v[196:197]
	v_pk_mul_f32 v[66:67], v[180:181], v[198:199]
	v_cvt_pk_bf16_f32 v64, v64, v65
	v_cvt_pk_bf16_f32 v65, v66, v67
	global_store_dwordx2 v173, v[64:65], s[8:9] offset:288
	v_fmac_f32_e32 v82, v178, v178
	v_fmac_f32_e32 v82, v179, v179
	v_fmac_f32_e32 v82, v180, v180
	v_fmac_f32_e32 v82, v181, v181
	v_add_u32_e32 v165, 0xa0000, v165
	v_lshrrev_b32_e32 v173, 1, v165
	global_load_dwordx4 v[178:181], v164, s[98:99] offset:576 nt
	v_add_u32_e32 v164, 0x20000, v164
	s_waitcnt vmcnt(21)
	v_pk_fma_f32 v[200:201], v[60:61], v[72:73], v[200:201]
	v_pk_fma_f32 v[202:203], v[62:63], v[74:75], v[202:203]
	global_store_dwordx4 v165, v[200:203], s[66:67]
	v_pk_mul_f32 v[60:61], v[200:201], v[182:183]
	v_pk_mul_f32 v[62:63], v[202:203], v[184:185]
	v_cvt_pk_bf16_f32 v60, v60, v61
	v_cvt_pk_bf16_f32 v61, v62, v63
	global_store_dwordx2 v173, v[60:61], s[8:9]
	v_mul_f32_e32 v62, v200, v200
	v_fmac_f32_e32 v62, v201, v201
	v_fmac_f32_e32 v62, v202, v202
	v_fmac_f32_e32 v62, v203, v203
	global_load_dwordx4 v[200:203], v164, s[98:99] nt
	s_waitcnt vmcnt(21)
	v_pk_fma_f32 v[204:205], v[56:57], v[84:85], v[204:205]
	v_pk_fma_f32 v[206:207], v[58:59], v[86:87], v[206:207]
	global_store_dwordx4 v165, v[204:207], s[66:67] offset:64
	v_pk_mul_f32 v[56:57], v[204:205], v[188:189]
	v_pk_mul_f32 v[58:59], v[206:207], v[190:191]
	v_cvt_pk_bf16_f32 v56, v56, v57
	v_cvt_pk_bf16_f32 v57, v58, v59
	global_store_dwordx2 v173, v[56:57], s[8:9] offset:32
	v_fmac_f32_e32 v62, v204, v204
	v_fmac_f32_e32 v62, v205, v205
	v_fmac_f32_e32 v62, v206, v206
	v_fmac_f32_e32 v62, v207, v207
	global_load_dwordx4 v[204:207], v164, s[98:99] offset:64 nt
	s_waitcnt vmcnt(21)
	v_pk_fma_f32 v[208:209], v[52:53], v[92:93], v[208:209]
	v_pk_fma_f32 v[210:211], v[54:55], v[94:95], v[210:211]
	global_store_dwordx4 v165, v[208:211], s[66:67] offset:512
	v_pk_mul_f32 v[52:53], v[208:209], v[192:193]
	v_pk_mul_f32 v[54:55], v[210:211], v[194:195]
	v_cvt_pk_bf16_f32 v52, v52, v53
	v_cvt_pk_bf16_f32 v53, v54, v55
	global_store_dwordx2 v173, v[52:53], s[8:9] offset:256
	v_fmac_f32_e32 v62, v208, v208
	v_fmac_f32_e32 v62, v209, v209
	v_fmac_f32_e32 v62, v210, v210
	v_fmac_f32_e32 v62, v211, v211
	global_load_dwordx4 v[208:211], v164, s[98:99] offset:512 nt
	s_waitcnt vmcnt(21)
	v_pk_fma_f32 v[212:213], v[48:49], v[96:97], v[212:213]
	v_pk_fma_f32 v[214:215], v[50:51], v[98:99], v[214:215]
	global_store_dwordx4 v165, v[212:215], s[66:67] offset:576
	v_pk_mul_f32 v[48:49], v[212:213], v[196:197]
	v_pk_mul_f32 v[50:51], v[214:215], v[198:199]
	v_cvt_pk_bf16_f32 v48, v48, v49
	v_cvt_pk_bf16_f32 v49, v50, v51
	global_store_dwordx2 v173, v[48:49], s[8:9] offset:288
	v_fmac_f32_e32 v62, v212, v212
	v_fmac_f32_e32 v62, v213, v213
	v_fmac_f32_e32 v62, v214, v214
	v_fmac_f32_e32 v62, v215, v215
	v_add_u32_e32 v165, 0x20000, v165
	v_lshrrev_b32_e32 v173, 1, v165
	global_load_dwordx4 v[212:215], v164, s[98:99] offset:576 nt
	v_add_u32_e32 v164, 0x20000, v164
	s_waitcnt vmcnt(21)
	v_pk_fma_f32 v[156:157], v[44:45], v[72:73], v[156:157]
	v_pk_fma_f32 v[158:159], v[46:47], v[74:75], v[158:159]
	global_store_dwordx4 v165, v[156:159], s[66:67]
	v_pk_mul_f32 v[44:45], v[156:157], v[182:183]
	v_pk_mul_f32 v[46:47], v[158:159], v[184:185]
	v_cvt_pk_bf16_f32 v44, v44, v45
	v_cvt_pk_bf16_f32 v45, v46, v47
	global_store_dwordx2 v173, v[44:45], s[8:9]
	v_mul_f32_e32 v46, v156, v156
	v_fmac_f32_e32 v46, v157, v157
	v_fmac_f32_e32 v46, v158, v158
	v_fmac_f32_e32 v46, v159, v159
	global_load_dwordx4 v[156:159], v164, s[98:99] nt
	s_waitcnt vmcnt(21)
	v_pk_fma_f32 v[160:161], v[40:41], v[84:85], v[160:161]
	v_pk_fma_f32 v[162:163], v[42:43], v[86:87], v[162:163]
	global_store_dwordx4 v165, v[160:163], s[66:67] offset:64
	v_pk_mul_f32 v[40:41], v[160:161], v[188:189]
	v_pk_mul_f32 v[42:43], v[162:163], v[190:191]
	v_cvt_pk_bf16_f32 v40, v40, v41
	v_cvt_pk_bf16_f32 v41, v42, v43
	global_store_dwordx2 v173, v[40:41], s[8:9] offset:32
	v_fmac_f32_e32 v46, v160, v160
	v_fmac_f32_e32 v46, v161, v161
	v_fmac_f32_e32 v46, v162, v162
	v_fmac_f32_e32 v46, v163, v163
	global_load_dwordx4 v[160:163], v164, s[98:99] offset:64 nt
	s_waitcnt vmcnt(21)
	v_pk_fma_f32 v[174:175], v[36:37], v[92:93], v[174:175]
	v_pk_fma_f32 v[176:177], v[38:39], v[94:95], v[176:177]
	global_store_dwordx4 v165, v[174:177], s[66:67] offset:512
	v_pk_mul_f32 v[36:37], v[174:175], v[192:193]
	v_pk_mul_f32 v[38:39], v[176:177], v[194:195]
	v_cvt_pk_bf16_f32 v36, v36, v37
	v_cvt_pk_bf16_f32 v37, v38, v39
	global_store_dwordx2 v173, v[36:37], s[8:9] offset:256
	v_fmac_f32_e32 v46, v174, v174
	v_fmac_f32_e32 v46, v175, v175
	v_fmac_f32_e32 v46, v176, v176
	v_fmac_f32_e32 v46, v177, v177
	global_load_dwordx4 v[174:177], v164, s[98:99] offset:512 nt
	s_waitcnt vmcnt(21)
; __device__ __forceinline__ unsigned cvt_pk_bf16(float lo, float hi) { unsigned r; asm volatile("v_cvt_pk_bf16_f32 %0, %1, %2" : "=v"(r) : "v"(lo), "v"(hi)); return r; }
;     __device__ __forceinline__ void operator()(const f32x4 (&acc)[2][2][4][2], const Unit& u, int wr, int wc, int fr, int fq) const {
;     ...
;             for (int m = 0; m < 4; ++m) { const int row = row0 + ai * HALF + m * 16; const size_t off = (size_t)row * 2048 + col0; float ss = 0.f;
; #pragma unroll
;                 for (int bj = 0; bj < 2; ++bj)
; #pragma unroll
;                     for (int n = 0; n < 2; ++n) { const f32x4 bs = __builtin_nontemporal_load((const f32x4*)(base + off + bj * HALF + n * 16)); const f32x4 x1 = bs + gv[bj][n] * acc[ai][bj][m][n];
;                         *(f32x4*)(out + off + bj * HALF + n * 16) = x1; ss += (x1.x * x1.x + x1.y * x1.y) + (x1.z * x1.z + x1.w * x1.w);
;                         const f32x4 hh = x1 * Gv[bj][n]; u32x2 w; w.x = cvt_pk_bf16(hh.x, hh.y); w.y = cvt_pk_bf16(hh.z, hh.w); *(u32x2*)(A2 + off + bj * HALF + n * 16) = w; }
;                 ss += __shfl_xor(ss, 16); ss += __shfl_xor(ss, 32);
;                 if (fq == 0) prow[row] = ss; }
	v_pk_fma_f32 v[178:179], v[32:33], v[96:97], v[178:179]
	v_pk_fma_f32 v[180:181], v[34:35], v[98:99], v[180:181]
	global_store_dwordx4 v165, v[178:181], s[66:67] offset:576
	v_pk_mul_f32 v[32:33], v[178:179], v[196:197]
	v_pk_mul_f32 v[34:35], v[180:181], v[198:199]
	v_cvt_pk_bf16_f32 v32, v32, v33
	v_cvt_pk_bf16_f32 v33, v34, v35
	global_store_dwordx2 v173, v[32:33], s[8:9] offset:288
	v_fmac_f32_e32 v46, v178, v178
	v_fmac_f32_e32 v46, v179, v179
	v_fmac_f32_e32 v46, v180, v180
	v_fmac_f32_e32 v46, v181, v181
	v_add_u32_e32 v165, 0x20000, v165
	v_lshrrev_b32_e32 v173, 1, v165
	global_load_dwordx4 v[178:181], v164, s[98:99] offset:576 nt
	s_waitcnt vmcnt(21)
	v_pk_fma_f32 v[200:201], v[28:29], v[72:73], v[200:201]
	v_pk_fma_f32 v[202:203], v[30:31], v[74:75], v[202:203]
	global_store_dwordx4 v165, v[200:203], s[66:67]
	v_pk_mul_f32 v[28:29], v[200:201], v[182:183]
	v_pk_mul_f32 v[30:31], v[202:203], v[184:185]
	v_cvt_pk_bf16_f32 v28, v28, v29
	v_cvt_pk_bf16_f32 v29, v30, v31
	global_store_dwordx2 v173, v[28:29], s[8:9]
	v_mul_f32_e32 v30, v200, v200
	v_fmac_f32_e32 v30, v201, v201
	v_fmac_f32_e32 v30, v202, v202
	v_fmac_f32_e32 v30, v203, v203
	s_waitcnt vmcnt(20)
	v_pk_fma_f32 v[204:205], v[24:25], v[84:85], v[204:205]
	v_pk_fma_f32 v[206:207], v[26:27], v[86:87], v[206:207]
	global_store_dwordx4 v165, v[204:207], s[66:67] offset:64
	v_pk_mul_f32 v[24:25], v[204:205], v[188:189]
	v_pk_mul_f32 v[26:27], v[206:207], v[190:191]
	v_cvt_pk_bf16_f32 v24, v24, v25
	v_cvt_pk_bf16_f32 v25, v26, v27
	global_store_dwordx2 v173, v[24:25], s[8:9] offset:32
	v_fmac_f32_e32 v30, v204, v204
	v_fmac_f32_e32 v30, v205, v205
	v_fmac_f32_e32 v30, v206, v206
	v_fmac_f32_e32 v30, v207, v207
	s_waitcnt vmcnt(19)
	v_pk_fma_f32 v[208:209], v[20:21], v[92:93], v[208:209]
	v_pk_fma_f32 v[210:211], v[22:23], v[94:95], v[210:211]
	global_store_dwordx4 v165, v[208:211], s[66:67] offset:512
	v_pk_mul_f32 v[20:21], v[208:209], v[192:193]
	v_pk_mul_f32 v[22:23], v[210:211], v[194:195]
	v_cvt_pk_bf16_f32 v20, v20, v21
	v_cvt_pk_bf16_f32 v21, v22, v23
	global_store_dwordx2 v173, v[20:21], s[8:9] offset:256
	v_fmac_f32_e32 v30, v208, v208
	v_fmac_f32_e32 v30, v209, v209
	v_fmac_f32_e32 v30, v210, v210
	v_fmac_f32_e32 v30, v211, v211
	s_waitcnt vmcnt(18)
	v_pk_fma_f32 v[212:213], v[16:17], v[96:97], v[212:213]
	v_pk_fma_f32 v[214:215], v[18:19], v[98:99], v[214:215]
	global_store_dwordx4 v165, v[212:215], s[66:67] offset:576
	v_pk_mul_f32 v[16:17], v[212:213], v[196:197]
	v_pk_mul_f32 v[18:19], v[214:215], v[198:199]
	v_cvt_pk_bf16_f32 v16, v16, v17
	v_cvt_pk_bf16_f32 v17, v18, v19
	global_store_dwordx2 v173, v[16:17], s[8:9] offset:288
	v_fmac_f32_e32 v30, v212, v212
	v_fmac_f32_e32 v30, v213, v213
	v_fmac_f32_e32 v30, v214, v214
	v_fmac_f32_e32 v30, v215, v215
	v_add_u32_e32 v165, 0x20000, v165
	v_lshrrev_b32_e32 v173, 1, v165
	s_waitcnt vmcnt(17)
	v_pk_fma_f32 v[156:157], v[12:13], v[72:73], v[156:157]
	v_pk_fma_f32 v[158:159], v[14:15], v[74:75], v[158:159]
	global_store_dwordx4 v165, v[156:159], s[66:67]
	v_pk_mul_f32 v[12:13], v[156:157], v[182:183]
	v_pk_mul_f32 v[14:15], v[158:159], v[184:185]
	v_cvt_pk_bf16_f32 v12, v12, v13
	v_cvt_pk_bf16_f32 v13, v14, v15
	global_store_dwordx2 v173, v[12:13], s[8:9]
	v_mul_f32_e32 v14, v156, v156
	v_fmac_f32_e32 v14, v157, v157
	v_fmac_f32_e32 v14, v158, v158
	v_fmac_f32_e32 v14, v159, v159
	s_waitcnt vmcnt(16)
	v_pk_fma_f32 v[160:161], v[8:9], v[84:85], v[160:161]
	v_pk_fma_f32 v[162:163], v[10:11], v[86:87], v[162:163]
	global_store_dwordx4 v165, v[160:163], s[66:67] offset:64
	v_pk_mul_f32 v[8:9], v[160:161], v[188:189]
	v_pk_mul_f32 v[10:11], v[162:163], v[190:191]
	v_cvt_pk_bf16_f32 v8, v8, v9
	v_cvt_pk_bf16_f32 v9, v10, v11
	global_store_dwordx2 v173, v[8:9], s[8:9] offset:32
	v_fmac_f32_e32 v14, v160, v160
	v_fmac_f32_e32 v14, v161, v161
	v_fmac_f32_e32 v14, v162, v162
	v_fmac_f32_e32 v14, v163, v163
	s_waitcnt vmcnt(15)
	v_pk_fma_f32 v[174:175], v[4:5], v[92:93], v[174:175]
	v_pk_fma_f32 v[176:177], v[6:7], v[94:95], v[176:177]
	global_store_dwordx4 v165, v[174:177], s[66:67] offset:512
	v_pk_mul_f32 v[4:5], v[174:175], v[192:193]
	v_pk_mul_f32 v[6:7], v[176:177], v[194:195]
	v_cvt_pk_bf16_f32 v4, v4, v5
	v_cvt_pk_bf16_f32 v5, v6, v7
	global_store_dwordx2 v173, v[4:5], s[8:9] offset:256
	v_fmac_f32_e32 v14, v174, v174
	v_fmac_f32_e32 v14, v175, v175
	v_fmac_f32_e32 v14, v176, v176
	v_fmac_f32_e32 v14, v177, v177
	s_waitcnt vmcnt(14)
	v_pk_fma_f32 v[178:179], v[0:1], v[96:97], v[178:179]
	v_pk_fma_f32 v[180:181], v[2:3], v[98:99], v[180:181]
	global_store_dwordx4 v165, v[178:181], s[66:67] offset:576
	v_pk_mul_f32 v[0:1], v[178:179], v[196:197]
	v_pk_mul_f32 v[2:3], v[180:181], v[198:199]
	v_cvt_pk_bf16_f32 v0, v0, v1
	v_cvt_pk_bf16_f32 v1, v2, v3
	global_store_dwordx2 v173, v[0:1], s[8:9] offset:288
	v_fmac_f32_e32 v14, v178, v178
	v_fmac_f32_e32 v14, v179, v179
	v_fmac_f32_e32 v14, v180, v180
	v_fmac_f32_e32 v14, v181, v181
	ds_bpermute_b32 v143, v216, v142
	ds_bpermute_b32 v127, v216, v126
	ds_bpermute_b32 v111, v216, v110
	ds_bpermute_b32 v83, v216, v82
	ds_bpermute_b32 v63, v216, v62
	ds_bpermute_b32 v47, v216, v46
	ds_bpermute_b32 v31, v216, v30
	ds_bpermute_b32 v15, v216, v14
	s_waitcnt lgkmcnt(0)
	v_add_f32_e32 v142, v142, v143
	v_add_f32_e32 v126, v126, v127
	v_add_f32_e32 v110, v110, v111
	v_add_f32_e32 v82, v82, v83
	v_add_f32_e32 v62, v62, v63
	v_add_f32_e32 v46, v46, v47
	v_add_f32_e32 v30, v30, v31
	v_add_f32_e32 v14, v14, v15
	ds_bpermute_b32 v143, v217, v142
	ds_bpermute_b32 v127, v217, v126
	ds_bpermute_b32 v111, v217, v110
	ds_bpermute_b32 v83, v217, v82
	ds_bpermute_b32 v63, v217, v62
	ds_bpermute_b32 v47, v217, v46
	ds_bpermute_b32 v31, v217, v30
	ds_bpermute_b32 v15, v217, v14
	s_lshl_b32 s25, s34, 2
	s_or_b32 s25, s25, s47
	s_lshl_b32 s25, s25, 16
	v_lshl_add_u32 v164, s36, 8, v166
	v_lshl_add_u32 v164, v164, 2, s25
	s_waitcnt lgkmcnt(0)
	v_add_f32_e32 v142, v142, v143
	v_add_f32_e32 v126, v126, v127
	v_add_f32_e32 v110, v110, v111
	v_add_f32_e32 v82, v82, v83
	v_add_f32_e32 v62, v62, v63
	v_add_f32_e32 v46, v46, v47
	v_add_f32_e32 v30, v30, v31
	v_add_f32_e32 v14, v14, v15
	s_and_saveexec_b64 s[100:101], s[4:5]
	global_store_dword v164, v142, s[48:49]
	global_store_dword v164, v126, s[48:49] offset:64
	global_store_dword v164, v110, s[48:49] offset:128
	global_store_dword v164, v82, s[48:49] offset:192
	global_store_dword v164, v62, s[48:49] offset:512
	global_store_dword v164, v46, s[48:49] offset:576
	global_store_dword v164, v30, s[48:49] offset:640
	global_store_dword v164, v14, s[48:49] offset:704
	s_or_b64 exec, exec, s[100:101]
	s_andn2_b64 vcc, exec, s[6:7]
	s_mov_b64 s[6:7], -1
	s_cbranch_vccnz .LBB0_886
	s_andn2_b64 vcc, exec, s[10:11]
	s_cbranch_vccnz .LBB0_885
	s_barrier
	s_branch .LBB0_885
